# grid barrier: non-leader L1 invalidate issued before the spin (overlaps the wait); plus hand-scheduled scan loops
# speedup vs baseline: 1.0344x; 1.0097x over previous
; __device__ __forceinline__ unsigned xb_ld(unsigned* p)              { return __hip_atomic_load(p, __ATOMIC_RELAXED, __HIP_MEMORY_SCOPE_AGENT); }
; __device__ __forceinline__ unsigned xb_add(unsigned* p, unsigned v) { return __hip_atomic_fetch_add(p, v, __ATOMIC_RELAXED, __HIP_MEMORY_SCOPE_AGENT); }
; #define XB_SPIN(cond, bar) do { unsigned _sp = 0; while (cond) { __builtin_amdgcn_s_sleep(1); \
;     if ((++_sp & 255u) == 0u) { if (xb_ld(&(bar)[XB_TMO])) break; if (_sp > XB_SPIN_CAP) { atomicAdd(&(bar)[XB_TMO], 1u); break; } } } } while (0)
; __device__ __forceinline__ void xcd_barrier(const XcdBarrier& b) {
;     ...
;         const unsigned old = xb_add(&bar[XB_XSUB(b.x)], 1u);
;         const unsigned gen = old / nloc;
;         if (old + 1u == (gen + 1u) * nloc) {
;             __builtin_amdgcn_fence(__ATOMIC_RELEASE, "agent");
;             asm volatile("s_waitcnt vmcnt(0)" ::: "memory");
;             const unsigned og = xb_add(&bar[XB_TOP], 1u);
;             const unsigned tg = og / nx;
;             if (og + 1u == (tg + 1u) * nx) xb_add(&bar[XB_TOPGEN], 1u);
;             else XB_SPIN(xb_ld(&bar[XB_TOPGEN]) == tg, bar);
;             __builtin_amdgcn_fence(__ATOMIC_ACQUIRE, "agent");
;             xb_add(&bar[XB_XGEN(b.x)], 1u);
;             asm volatile("s_waitcnt vmcnt(0)" ::: "memory");
;         } else {
;             XB_SPIN(xb_ld(&bar[XB_XGEN(b.x)]) == gen, bar);
.LBB0_144:
	s_or_b64 exec, exec, s[4:5]
	v_cvt_f32_u32_e32 v5, v2
	s_waitcnt vmcnt(0)
	v_readfirstlane_b32 s4, v4
	v_sub_u32_e32 v4, 0, v2
	v_rcp_iflag_f32_e32 v5, v5
	v_add_u32_e32 v6, s4, v1
	v_mul_f32_e32 v5, 0x4f7ffffe, v5
	v_cvt_u32_f32_e32 v5, v5
	v_mul_lo_u32 v1, v4, v5
	v_mul_hi_u32 v1, v5, v1
	v_add_u32_e32 v1, v5, v1
	v_mul_hi_u32 v1, v6, v1
	v_mul_lo_u32 v4, v1, v2
	v_sub_u32_e32 v4, v6, v4
	v_add_u32_e32 v5, 1, v1
	v_cmp_ge_u32_e32 vcc, v4, v2
	s_nop 1
	v_cndmask_b32_e32 v1, v1, v5, vcc
	v_sub_u32_e32 v5, v4, v2
	v_cndmask_b32_e32 v4, v4, v5, vcc
	v_add_u32_e32 v5, 1, v1
	v_cmp_ge_u32_e32 vcc, v4, v2
	v_add_u32_e32 v4, 1, v6
	s_nop 0
	v_cndmask_b32_e32 v1, v1, v5, vcc
	v_mul_lo_u32 v5, v2, v1
	v_add_u32_e32 v2, v5, v2
	v_cmp_ne_u32_e32 vcc, v4, v2
	s_and_saveexec_b64 s[4:5], vcc
	s_xor_b64 s[4:5], exec, s[4:5]
	s_cbranch_execz .LBB0_158
	v_readlane_b32 s28, v252, 20
	v_readlane_b32 s29, v252, 21
	s_waitcnt lgkmcnt(0)
	s_nop 3
	buffer_inv sc1
	global_load_dword v0, v3, s[28:29] sc1
	s_waitcnt vmcnt(0)
	v_cmp_eq_u32_e32 vcc, v0, v1
	s_and_saveexec_b64 s[28:29], vcc
	s_cbranch_execz .LBB0_157
	s_mov_b32 s48, 1
	s_mov_b64 s[34:35], 0
	s_branch .LBB0_148

; __device__ __forceinline__ unsigned xb_ld(unsigned* p)              { return __hip_atomic_load(p, __ATOMIC_RELAXED, __HIP_MEMORY_SCOPE_AGENT); }
; #define XB_SPIN(cond, bar) do { unsigned _sp = 0; while (cond) { __builtin_amdgcn_s_sleep(1); \
;     if ((++_sp & 255u) == 0u) { if (xb_ld(&(bar)[XB_TMO])) break; if (_sp > XB_SPIN_CAP) { atomicAdd(&(bar)[XB_TMO], 1u); break; } } } } while (0)
; __device__ __forceinline__ void xcd_barrier(const XcdBarrier& b) {
;     ...
;             XB_SPIN(xb_ld(&bar[XB_XGEN(b.x)]) == gen, bar);
;             __builtin_amdgcn_fence(__ATOMIC_ACQUIRE, "agent");
;             asm volatile("s_waitcnt vmcnt(0)" ::: "memory");
.LBB0_157:
	s_or_b64 exec, exec, s[28:29]
	s_waitcnt vmcnt(0)
	s_waitcnt vmcnt(0)

; __device__ __forceinline__ unsigned xb_ld(unsigned* p)              { return __hip_atomic_load(p, __ATOMIC_RELAXED, __HIP_MEMORY_SCOPE_AGENT); }
; __device__ __forceinline__ unsigned xb_add(unsigned* p, unsigned v) { return __hip_atomic_fetch_add(p, v, __ATOMIC_RELAXED, __HIP_MEMORY_SCOPE_AGENT); }
; #define XB_SPIN(cond, bar) do { unsigned _sp = 0; while (cond) { __builtin_amdgcn_s_sleep(1); \
;     if ((++_sp & 255u) == 0u) { if (xb_ld(&(bar)[XB_TMO])) break; if (_sp > XB_SPIN_CAP) { atomicAdd(&(bar)[XB_TMO], 1u); break; } } } } while (0)
; __device__ __forceinline__ void xcd_barrier(const XcdBarrier& b) {
;     ...
;         const unsigned old = xb_add(&bar[XB_XSUB(b.x)], 1u);
;         const unsigned gen = old / nloc;
;         if (old + 1u == (gen + 1u) * nloc) {
;             __builtin_amdgcn_fence(__ATOMIC_RELEASE, "agent");
;             asm volatile("s_waitcnt vmcnt(0)" ::: "memory");
;             const unsigned og = xb_add(&bar[XB_TOP], 1u);
;             const unsigned tg = og / nx;
;             if (og + 1u == (tg + 1u) * nx) xb_add(&bar[XB_TOPGEN], 1u);
;             else XB_SPIN(xb_ld(&bar[XB_TOPGEN]) == tg, bar);
;             __builtin_amdgcn_fence(__ATOMIC_ACQUIRE, "agent");
;             xb_add(&bar[XB_XGEN(b.x)], 1u);
;             asm volatile("s_waitcnt vmcnt(0)" ::: "memory");
;         } else {
;             XB_SPIN(xb_ld(&bar[XB_XGEN(b.x)]) == gen, bar);
.LBB0_218:
	s_or_b64 exec, exec, s[4:5]
	v_cvt_f32_u32_e32 v5, v2
	s_waitcnt vmcnt(0)
	v_readfirstlane_b32 s4, v4
	v_sub_u32_e32 v4, 0, v2
	v_rcp_iflag_f32_e32 v5, v5
	v_add_u32_e32 v6, s4, v1
	v_mul_f32_e32 v5, 0x4f7ffffe, v5
	v_cvt_u32_f32_e32 v5, v5
	v_mul_lo_u32 v1, v4, v5
	v_mul_hi_u32 v1, v5, v1
	v_add_u32_e32 v1, v5, v1
	v_mul_hi_u32 v1, v6, v1
	v_mul_lo_u32 v4, v1, v2
	v_sub_u32_e32 v4, v6, v4
	v_add_u32_e32 v5, 1, v1
	v_cmp_ge_u32_e32 vcc, v4, v2
	s_nop 1
	v_cndmask_b32_e32 v1, v1, v5, vcc
	v_sub_u32_e32 v5, v4, v2
	v_cndmask_b32_e32 v4, v4, v5, vcc
	v_add_u32_e32 v5, 1, v1
	v_cmp_ge_u32_e32 vcc, v4, v2
	v_add_u32_e32 v4, 1, v6
	s_nop 0
	v_cndmask_b32_e32 v1, v1, v5, vcc
	v_mul_lo_u32 v5, v2, v1
	v_add_u32_e32 v2, v5, v2
	v_cmp_ne_u32_e32 vcc, v4, v2
	s_and_saveexec_b64 s[4:5], vcc
	s_xor_b64 s[4:5], exec, s[4:5]
	s_cbranch_execz .LBB0_232
	v_readlane_b32 s28, v252, 20
	v_readlane_b32 s29, v252, 21
	s_waitcnt lgkmcnt(0)
	s_nop 3
	buffer_inv sc1
	global_load_dword v0, v3, s[28:29] sc1
	s_waitcnt vmcnt(0)
	v_cmp_eq_u32_e32 vcc, v0, v1
	s_and_saveexec_b64 s[28:29], vcc
	s_cbranch_execz .LBB0_231
	s_mov_b32 s50, 1
	s_mov_b64 s[34:35], 0
	s_branch .LBB0_222

; __device__ __forceinline__ unsigned xb_ld(unsigned* p)              { return __hip_atomic_load(p, __ATOMIC_RELAXED, __HIP_MEMORY_SCOPE_AGENT); }
; __device__ __forceinline__ unsigned xb_add(unsigned* p, unsigned v) { return __hip_atomic_fetch_add(p, v, __ATOMIC_RELAXED, __HIP_MEMORY_SCOPE_AGENT); }
; #define XB_SPIN(cond, bar) do { unsigned _sp = 0; while (cond) { __builtin_amdgcn_s_sleep(1); \
;     if ((++_sp & 255u) == 0u) { if (xb_ld(&(bar)[XB_TMO])) break; if (_sp > XB_SPIN_CAP) { atomicAdd(&(bar)[XB_TMO], 1u); break; } } } } while (0)
; __device__ __forceinline__ void xcd_barrier(const XcdBarrier& b) {
;     ...
;         const unsigned old = xb_add(&bar[XB_XSUB(b.x)], 1u);
;         const unsigned gen = old / nloc;
;         if (old + 1u == (gen + 1u) * nloc) {
;             __builtin_amdgcn_fence(__ATOMIC_RELEASE, "agent");
;             asm volatile("s_waitcnt vmcnt(0)" ::: "memory");
;             const unsigned og = xb_add(&bar[XB_TOP], 1u);
;             const unsigned tg = og / nx;
;             if (og + 1u == (tg + 1u) * nx) xb_add(&bar[XB_TOPGEN], 1u);
;             else XB_SPIN(xb_ld(&bar[XB_TOPGEN]) == tg, bar);
;             __builtin_amdgcn_fence(__ATOMIC_ACQUIRE, "agent");
;             xb_add(&bar[XB_XGEN(b.x)], 1u);
;             asm volatile("s_waitcnt vmcnt(0)" ::: "memory");
;         } else {
;             XB_SPIN(xb_ld(&bar[XB_XGEN(b.x)]) == gen, bar);
.LBB0_418:
	s_or_b64 exec, exec, s[4:5]
	v_cvt_f32_u32_e32 v5, v2
	s_waitcnt vmcnt(0)
	v_readfirstlane_b32 s2, v4
	v_sub_u32_e32 v4, 0, v2
	v_rcp_iflag_f32_e32 v5, v5
	v_add_u32_e32 v6, s2, v1
	v_mul_f32_e32 v5, 0x4f7ffffe, v5
	v_cvt_u32_f32_e32 v5, v5
	v_mul_lo_u32 v1, v4, v5
	v_mul_hi_u32 v1, v5, v1
	v_add_u32_e32 v1, v5, v1
	v_mul_hi_u32 v1, v6, v1
	v_mul_lo_u32 v4, v1, v2
	v_sub_u32_e32 v4, v6, v4
	v_add_u32_e32 v5, 1, v1
	v_cmp_ge_u32_e32 vcc, v4, v2
	s_nop 1
	v_cndmask_b32_e32 v1, v1, v5, vcc
	v_sub_u32_e32 v5, v4, v2
	v_cndmask_b32_e32 v4, v4, v5, vcc
	v_add_u32_e32 v5, 1, v1
	v_cmp_ge_u32_e32 vcc, v4, v2
	v_add_u32_e32 v4, 1, v6
	s_nop 0
	v_cndmask_b32_e32 v1, v1, v5, vcc
	v_mul_lo_u32 v5, v2, v1
	v_add_u32_e32 v2, v5, v2
	v_cmp_ne_u32_e32 vcc, v4, v2
	s_and_saveexec_b64 s[4:5], vcc
	s_xor_b64 s[4:5], exec, s[4:5]
	s_cbranch_execz .LBB0_432
	v_readlane_b32 s28, v252, 20
	v_readlane_b32 s29, v252, 21
	s_waitcnt lgkmcnt(0)
	s_nop 3
	buffer_inv sc1
	global_load_dword v0, v3, s[28:29] sc1
	s_waitcnt vmcnt(0)
	v_cmp_eq_u32_e32 vcc, v0, v1
	s_and_saveexec_b64 s[28:29], vcc
	s_cbranch_execz .LBB0_431
	s_mov_b32 s2, 1
	s_mov_b64 s[34:35], 0
	s_branch .LBB0_422

; __device__ __forceinline__ unsigned xb_ld(unsigned* p)              { return __hip_atomic_load(p, __ATOMIC_RELAXED, __HIP_MEMORY_SCOPE_AGENT); }
; __device__ __forceinline__ unsigned xb_add(unsigned* p, unsigned v) { return __hip_atomic_fetch_add(p, v, __ATOMIC_RELAXED, __HIP_MEMORY_SCOPE_AGENT); }
; #define XB_SPIN(cond, bar) do { unsigned _sp = 0; while (cond) { __builtin_amdgcn_s_sleep(1); \
;     if ((++_sp & 255u) == 0u) { if (xb_ld(&(bar)[XB_TMO])) break; if (_sp > XB_SPIN_CAP) { atomicAdd(&(bar)[XB_TMO], 1u); break; } } } } while (0)
; __device__ __forceinline__ void xcd_barrier(const XcdBarrier& b) {
;     ...
;         const unsigned old = xb_add(&bar[XB_XSUB(b.x)], 1u);
;         const unsigned gen = old / nloc;
;         if (old + 1u == (gen + 1u) * nloc) {
;             __builtin_amdgcn_fence(__ATOMIC_RELEASE, "agent");
;             asm volatile("s_waitcnt vmcnt(0)" ::: "memory");
;             const unsigned og = xb_add(&bar[XB_TOP], 1u);
;             const unsigned tg = og / nx;
;             if (og + 1u == (tg + 1u) * nx) xb_add(&bar[XB_TOPGEN], 1u);
;             else XB_SPIN(xb_ld(&bar[XB_TOPGEN]) == tg, bar);
;             __builtin_amdgcn_fence(__ATOMIC_ACQUIRE, "agent");
;             xb_add(&bar[XB_XGEN(b.x)], 1u);
;             asm volatile("s_waitcnt vmcnt(0)" ::: "memory");
;         } else {
;             XB_SPIN(xb_ld(&bar[XB_XGEN(b.x)]) == gen, bar);
.LBB0_502:
	s_or_b64 exec, exec, s[4:5]
	v_cvt_f32_u32_e32 v5, v2
	s_waitcnt vmcnt(0)
	v_readfirstlane_b32 s4, v4
	v_sub_u32_e32 v4, 0, v2
	v_rcp_iflag_f32_e32 v5, v5
	v_add_u32_e32 v6, s4, v1
	v_mul_f32_e32 v5, 0x4f7ffffe, v5
	v_cvt_u32_f32_e32 v5, v5
	v_mul_lo_u32 v1, v4, v5
	v_mul_hi_u32 v1, v5, v1
	v_add_u32_e32 v1, v5, v1
	v_mul_hi_u32 v1, v6, v1
	v_mul_lo_u32 v4, v1, v2
	v_sub_u32_e32 v4, v6, v4
	v_add_u32_e32 v5, 1, v1
	v_cmp_ge_u32_e32 vcc, v4, v2
	s_nop 1
	v_cndmask_b32_e32 v1, v1, v5, vcc
	v_sub_u32_e32 v5, v4, v2
	v_cndmask_b32_e32 v4, v4, v5, vcc
	v_add_u32_e32 v5, 1, v1
	v_cmp_ge_u32_e32 vcc, v4, v2
	v_add_u32_e32 v4, 1, v6
	s_nop 0
	v_cndmask_b32_e32 v1, v1, v5, vcc
	v_mul_lo_u32 v5, v2, v1
	v_add_u32_e32 v2, v5, v2
	v_cmp_ne_u32_e32 vcc, v4, v2
	s_and_saveexec_b64 s[4:5], vcc
	s_xor_b64 s[4:5], exec, s[4:5]
	s_cbranch_execz .LBB0_516
	v_readlane_b32 s28, v252, 20
	v_readlane_b32 s29, v252, 21
	s_waitcnt lgkmcnt(0)
	s_nop 3
	buffer_inv sc1
	global_load_dword v0, v3, s[28:29] sc1
	s_waitcnt vmcnt(0)
	v_cmp_eq_u32_e32 vcc, v0, v1
	s_and_saveexec_b64 s[28:29], vcc
	s_cbranch_execz .LBB0_515
	s_mov_b32 s46, 1
	s_mov_b64 s[34:35], 0
	s_branch .LBB0_506
